# gate: next item's query rows loaded during the current item's top-k/appends
# speedup vs baseline: 1.0037x; 1.0007x over previous
.LBB0_267:
	s_and_b64 vcc, exec, s[6:7]
	s_cbranch_vccz .LBB0_503
	s_waitcnt vmcnt(0)
	v_mov_b32_e32 v40, v156
	s_mov_b32 s39, s79
	s_cmpk_gt_i32 s39, 0x3ff
	s_cbranch_scc1 .LBB0_503
	s_load_dwordx2 s[8:9], s[92:93], 0xa8
	s_waitcnt vmcnt(7)
	v_bfe_u32 v3, v40, 4, 2
	v_lshlrev_b32_e32 v158, 4, v3
	s_add_u32 s24, s90, 0x4940000
	v_ashrrev_i32_e32 v0, 2, v40
	s_waitcnt lgkmcnt(0)
	v_lshl_add_u64 v[32:33], s[8:9], 0, v[158:159]
	v_lshlrev_b32_e32 v158, 5, v3
	s_addc_u32 s25, s91, 0
	v_and_b32_e32 v2, 15, v40
	v_bfi_b32 v42, -16, v0, v40
	v_lshl_add_u64 v[0:1], s[90:91], 0, v[158:159]
	s_mov_b64 s[0:1], 0x4900000
	s_add_u32 s88, s90, 0xec00000
	v_lshl_add_u64 v[34:35], v[0:1], 0, s[0:1]
	v_lshlrev_b32_e32 v46, 2, v3
	v_lshlrev_b32_e32 v0, 7, v2
	s_addc_u32 s89, s91, 0
	v_cmp_gt_i32_e64 s[6:7], 64, v40
	v_lshl_add_u32 v41, v40, 2, 0
	v_or_b32_e32 v43, 0x3e8, v3
	v_or_b32_e32 v44, 0x7d0, v3
	v_or_b32_e32 v45, 0xbb8, v3
	v_cmp_eq_u32_e64 s[8:9], 0, v3
	v_or_b32_e32 v47, 1, v46
	v_or_b32_e32 v48, 2, v46
	v_or_b32_e32 v49, 3, v46
	v_or_b32_e32 v50, 16, v46
	v_or_b32_e32 v51, 17, v46
	s_waitcnt vmcnt(6)
	v_or_b32_e32 v52, 18, v46
	v_or_b32_e32 v53, 19, v46
	v_or_b32_e32 v54, 32, v46
	v_or_b32_e32 v55, 33, v46
	s_waitcnt vmcnt(0)
	v_or_b32_e32 v56, 34, v46
	v_or_b32_e32 v57, 35, v46
	v_or_b32_e32 v58, 48, v46
	v_or_b32_e32 v59, 49, v46
	v_or_b32_e32 v60, 50, v46
	v_or_b32_e32 v61, 51, v46
	s_lshl_b32 s47, s39, 4
	v_lshlrev_b32_e32 v62, 2, v0
	s_mov_b32 s32, s39
	s_mov_b32 s37, s47
	s_and_b32 s37, s37, 0xffffff80
	s_and_b32 s32, s32, 7
	s_lshl_b32 s32, s32, 14
	v_add_u32_e32 v92, s37, v42
	v_mov_b32_e32 v93, 0
	v_add_u32_e32 v92, s32, v92
	v_lshlrev_b64 v[92:93], 8, v[92:93]
	v_lshl_add_u64 v[92:93], v[32:33], 0, v[92:93]
	global_load_dwordx4 v[76:79], v[92:93], off
	global_load_dwordx4 v[80:83], v[92:93], off offset:64
	global_load_dwordx4 v[84:87], v[92:93], off offset:128
	global_load_dwordx4 v[88:91], v[92:93], off offset:192
	s_branch .LBB0_271

.LBB0_271:
	s_barrier
	s_and_saveexec_b64 s[10:11], s[6:7]
	ds_write_b32 v41, v159
	s_or_b64 exec, exec, s[10:11]
	s_and_b32 s0, s47, 0xffffff80
	s_and_b32 s72, s39, 7
	v_add_u32_e32 v36, s0, v42
	s_lshl_b32 s48, s72, 14
	v_ashrrev_i32_e32 v37, 31, v36
	v_lshl_add_u64 v[0:1], v[36:37], 0, s[48:49]
	v_lshlrev_b64 v[0:1], 8, v[0:1]
	v_lshl_add_u64 v[0:1], v[32:33], 0, v[0:1]
	s_waitcnt lgkmcnt(0)
	s_barrier
	s_waitcnt vmcnt(0)
	v_mov_b32_e32 v20, v76
	v_mov_b32_e32 v21, v77
	v_mov_b32_e32 v22, v78
	v_mov_b32_e32 v23, v79
	v_mov_b32_e32 v16, v80
	v_mov_b32_e32 v17, v81
	v_mov_b32_e32 v18, v82
	v_mov_b32_e32 v19, v83
	v_mov_b32_e32 v12, v84
	v_mov_b32_e32 v13, v85
	v_mov_b32_e32 v14, v86
	v_mov_b32_e32 v15, v87
	v_mov_b32_e32 v0, v88
	v_mov_b32_e32 v1, v89
	v_mov_b32_e32 v2, v90
	v_mov_b32_e32 v3, v91
	s_ashr_i32 s48, s39, 4
	s_add_i32 s0, s48, 15
	s_ashr_i32 s0, s0, 4
	v_mov_b32_e32 v4, 0
	s_cmp_lt_i32 s0, 1
	v_lshl_or_b32 v158, s72, 15, v62
	v_mov_b32_e32 v8, 0
	v_mov_b32_e32 v9, 0
	v_mov_b32_e32 v10, 0
	v_mov_b32_e32 v11, 0
	s_cbranch_scc1 .LBB0_275
	v_lshl_add_u64 v[6:7], v[34:35], 0, v[158:159]
	global_load_dwordx4 v[8:11], v[6:7], off offset:16
	global_load_dwordx4 v[24:27], v[6:7], off
	s_waitcnt vmcnt(0)
	v_cvt_pk_bf16_f32 v28, v24, v25
	s_nop 0
	v_lshlrev_b32_e32 v5, 16, v28
	v_sub_f32_e32 v5, v24, v5
	v_and_b32_e32 v24, 0xffff0000, v28
	v_sub_f32_e32 v24, v25, v24
	v_cvt_pk_bf16_f32 v29, v26, v27
	v_cvt_pk_bf16_f32 v30, v8, v9
	v_cvt_pk_bf16_f32 v31, v10, v11
	v_cvt_pk_bf16_f32 v24, v5, v24
	s_nop 0
	v_lshlrev_b32_e32 v5, 16, v29
	v_and_b32_e32 v25, 0xffff0000, v29
	v_sub_f32_e32 v5, v26, v5
	v_sub_f32_e32 v25, v27, v25
	v_cvt_pk_bf16_f32 v25, v5, v25
	v_lshlrev_b32_e32 v5, 16, v30
	v_sub_f32_e32 v5, v8, v5
	v_and_b32_e32 v8, 0xffff0000, v30
	v_sub_f32_e32 v8, v9, v8
	v_cvt_pk_bf16_f32 v26, v5, v8
	v_and_b32_e32 v8, 0xffff0000, v31
	v_lshlrev_b32_e32 v5, 16, v31
	v_sub_f32_e32 v8, v11, v8
	v_sub_f32_e32 v5, v10, v5
	v_cvt_pk_bf16_f32 v27, v5, v8
	v_mfma_f32_16x16x32_bf16 v[8:11], v[28:31], v[20:23], 0
	v_mfma_f32_16x16x32_bf16 v[8:11], v[24:27], v[20:23], v[8:11]
	global_load_dwordx4 v[24:27], v[6:7], off offset:144
	global_load_dwordx4 v[28:31], v[6:7], off offset:128
	s_waitcnt vmcnt(0)
	v_cvt_pk_bf16_f32 v64, v28, v29
	s_nop 0
	v_lshlrev_b32_e32 v5, 16, v64
	v_sub_f32_e32 v5, v28, v5
	v_and_b32_e32 v28, 0xffff0000, v64
	v_sub_f32_e32 v28, v29, v28
	v_cvt_pk_bf16_f32 v65, v30, v31
	v_cvt_pk_bf16_f32 v66, v24, v25
	v_cvt_pk_bf16_f32 v67, v26, v27
	v_cvt_pk_bf16_f32 v28, v5, v28
	s_nop 0
	v_lshlrev_b32_e32 v5, 16, v65
	v_and_b32_e32 v29, 0xffff0000, v65
	v_sub_f32_e32 v5, v30, v5
	v_sub_f32_e32 v29, v31, v29
	v_cvt_pk_bf16_f32 v29, v5, v29
	v_lshlrev_b32_e32 v5, 16, v66
	v_sub_f32_e32 v5, v24, v5
	v_and_b32_e32 v24, 0xffff0000, v66
	v_mfma_f32_16x16x32_bf16 v[8:11], v[64:67], v[16:19], v[8:11]
	v_sub_f32_e32 v24, v25, v24
	v_cvt_pk_bf16_f32 v30, v5, v24
	v_lshlrev_b32_e32 v5, 16, v67
	v_and_b32_e32 v24, 0xffff0000, v67
	v_sub_f32_e32 v5, v26, v5
	v_sub_f32_e32 v24, v27, v24
	v_cvt_pk_bf16_f32 v31, v5, v24
	s_nop 0
	v_mfma_f32_16x16x32_bf16 v[8:11], v[28:31], v[16:19], v[8:11]
	global_load_dwordx4 v[24:27], v[6:7], off offset:272
	global_load_dwordx4 v[28:31], v[6:7], off offset:256
	s_waitcnt vmcnt(0)
	v_cvt_pk_bf16_f32 v64, v28, v29
	s_nop 0
	v_lshlrev_b32_e32 v5, 16, v64
	v_sub_f32_e32 v5, v28, v5
	v_and_b32_e32 v28, 0xffff0000, v64
	v_sub_f32_e32 v28, v29, v28
	v_cvt_pk_bf16_f32 v65, v30, v31
	v_cvt_pk_bf16_f32 v66, v24, v25
	v_cvt_pk_bf16_f32 v67, v26, v27
	v_cvt_pk_bf16_f32 v28, v5, v28
	s_nop 0
	v_lshlrev_b32_e32 v5, 16, v65
	v_and_b32_e32 v29, 0xffff0000, v65
	v_sub_f32_e32 v5, v30, v5
	v_sub_f32_e32 v29, v31, v29
	v_cvt_pk_bf16_f32 v29, v5, v29
	v_lshlrev_b32_e32 v5, 16, v66
	v_sub_f32_e32 v5, v24, v5
	v_and_b32_e32 v24, 0xffff0000, v66
	v_mfma_f32_16x16x32_bf16 v[8:11], v[64:67], v[12:15], v[8:11]
	v_sub_f32_e32 v24, v25, v24
	v_cvt_pk_bf16_f32 v30, v5, v24
	v_lshlrev_b32_e32 v5, 16, v67
	v_and_b32_e32 v24, 0xffff0000, v67
	v_sub_f32_e32 v5, v26, v5
	v_sub_f32_e32 v24, v27, v24
	v_cvt_pk_bf16_f32 v31, v5, v24
	s_nop 0
	v_mfma_f32_16x16x32_bf16 v[8:11], v[28:31], v[12:15], v[8:11]
	global_load_dwordx4 v[24:27], v[6:7], off offset:400
	global_load_dwordx4 v[28:31], v[6:7], off offset:384
	s_waitcnt vmcnt(0)
	v_cvt_pk_bf16_f32 v64, v28, v29
	s_nop 0
	v_and_b32_e32 v6, 0xffff0000, v64
	v_lshlrev_b32_e32 v5, 16, v64
	v_sub_f32_e32 v6, v29, v6
	v_cvt_pk_bf16_f32 v65, v30, v31
	v_cvt_pk_bf16_f32 v66, v24, v25
	v_cvt_pk_bf16_f32 v67, v26, v27
	v_sub_f32_e32 v5, v28, v5
	v_cvt_pk_bf16_f32 v28, v5, v6
	v_and_b32_e32 v6, 0xffff0000, v65
	v_lshlrev_b32_e32 v5, 16, v65
	v_sub_f32_e32 v6, v31, v6
	v_sub_f32_e32 v5, v30, v5
	v_cvt_pk_bf16_f32 v29, v5, v6
	v_and_b32_e32 v6, 0xffff0000, v66
	v_lshlrev_b32_e32 v5, 16, v66
	v_sub_f32_e32 v6, v25, v6
	v_sub_f32_e32 v5, v24, v5
	v_cvt_pk_bf16_f32 v30, v5, v6
	v_and_b32_e32 v6, 0xffff0000, v67
	v_lshlrev_b32_e32 v5, 16, v67
	v_sub_f32_e32 v6, v27, v6
	v_sub_f32_e32 v5, v26, v5
	v_cvt_pk_bf16_f32 v31, v5, v6
	v_mfma_f32_16x16x32_bf16 v[6:9], v[64:67], v[0:3], v[8:11]
	v_mfma_f32_16x16x32_bf16 v[8:11], v[28:31], v[0:3], v[6:9]

.LBB0_281:
	v_cmp_gt_i32_e32 vcc, s48, v46
	s_waitcnt vmcnt(0)
	s_add_i32 s32, s39, s34
	s_add_i32 s37, s47, s83
	s_cmpk_gt_i32 s32, 0x3ff
	s_cselect_b32 s32, s39, s32
	s_cselect_b32 s37, s47, s37
	s_and_b32 s37, s37, 0xffffff80
	s_and_b32 s32, s32, 7
	s_lshl_b32 s32, s32, 14
	v_add_u32_e32 v92, s37, v42
	v_mov_b32_e32 v93, 0
	v_add_u32_e32 v92, s32, v92
	v_lshlrev_b64 v[92:93], 8, v[92:93]
	v_lshl_add_u64 v[92:93], v[32:33], 0, v[92:93]
	global_load_dwordx4 v[76:79], v[92:93], off
	global_load_dwordx4 v[80:83], v[92:93], off offset:64
	global_load_dwordx4 v[84:87], v[92:93], off offset:128
	global_load_dwordx4 v[88:91], v[92:93], off offset:192
	v_mov_b32_e32 v1, 0xff800000
	v_mov_b32_e32 v2, 0xff800000
	v_mov_b32_e32 v3, v43
	v_mov_b32_e32 v0, v44
	v_mov_b32_e32 v12, v45
	s_and_saveexec_b64 s[10:11], vcc
	s_cbranch_execz .LBB0_285
	s_mov_b32 s0, 0xff800000
	v_cmp_nlg_f32_e32 vcc, s0, v8
	v_mov_b32_e32 v12, v44
	v_mov_b32_e32 v0, v43
	v_mov_b32_e32 v3, v46
	s_and_saveexec_b64 s[58:59], vcc
	v_mov_b32_e32 v8, 0xff800000
	v_mov_b32_e32 v12, v45
	v_mov_b32_e32 v0, v44
	v_mov_b32_e32 v3, v43
	s_or_b64 exec, exec, s[58:59]
	v_mov_b32_e32 v2, v8
